# adds: G1 first load segment ds_reads hoisted above next-unit arithmetic and restore barrier
# baseline (speedup 1.0000x reference)
.LBB0_65:
	s_add_i32 s60, 0, 0x10000
	s_add_i32 s63, 0, 0x14000
	v_add_u32_e32 v154, s60, v172
	v_add_u32_e32 v176, s63, v172
	ds_read_b128 v[130:133], v154
	ds_read_b128 v[146:149], v154 offset:1024
	ds_read_b128 v[150:153], v154 offset:2048
	ds_read_b128 v[154:157], v154 offset:3072
	ds_read_b128 v[158:161], v176
	ds_read_b128 v[162:165], v176 offset:1024
	ds_read_b128 v[168:171], v176 offset:2048
	ds_read_b128 v[176:179], v176 offset:3072
	ds_read_b128 v[180:183], v175
	ds_read_b128 v[184:187], v175 offset:1024
	ds_read_b128 v[188:191], v175 offset:2048
	ds_read_b128 v[192:195], v175 offset:3072
	ds_read_b128 v[196:199], v175 offset:4096
	ds_read_b128 v[200:203], v175 offset:5120
	ds_read_b128 v[204:207], v175 offset:6144
	ds_read_b128 v[216:219], v175 offset:7168
	s_add_i32 s50, s50, 1
	v_readlane_b32 s13, v254, 3
	s_mul_i32 s13, s50, s13
	s_mul_hi_u32 s15, s50, s54
	s_add_i32 s15, s15, s13
	s_mul_i32 s13, s50, s54
	s_add_u32 s16, s13, s72
	s_addc_u32 s17, s15, s36
	v_mov_b64_e32 v[0:1], 0x1600
	v_cmp_lt_i64_e64 s[42:43], s[16:17], v[0:1]
	v_mov_b64_e32 v[0:1], 0x15ff
	v_cmp_gt_i64_e32 vcc, s[16:17], v[0:1]
	s_cbranch_vccnz .LBB0_67
	s_ashr_i32 s12, s16, 31
	s_lshr_b32 s12, s12, 29
	s_add_i32 s12, s16, s12
	s_ashr_i32 s13, s12, 3
	s_and_b32 s12, s12, -8
	s_sub_i32 s12, s16, s12
	s_cmp_lt_i32 s12, 0
	s_movk_i32 s14, 0x2c1
	s_cselect_b32 s14, s14, 0x2c0
	s_mul_i32 s12, s12, s14
	s_add_i32 s12, s12, s13
	s_mul_hi_i32 s13, s12, 0x2e8ba2e9
	s_lshr_b32 s14, s13, 31
	s_ashr_i32 s13, s13, 5
	s_add_i32 s13, s13, s14
	s_lshl_b32 s14, s13, 3
	s_mulk_i32 s13, 0xb0
	s_sub_i32 s13, s12, s13
	s_lshr_b32 s12, s13, 3
	s_and_b32 s13, s13, 7
	s_add_i32 s14, s14, s13

.Lrb68_skip:
	s_add_u32 s24, s22, 0xfffc0080
	s_addc_u32 s25, s23, -1
	s_cmp_eq_u32 s57, 12
	s_cselect_b32 s27, s15, s25
	s_cselect_b32 s26, s21, s24
	s_cselect_b32 s25, s13, s56
	s_cselect_b32 s24, s33, s55
	v_lshl_add_u64 v[208:209], s[22:23], 0, v[142:143]
	s_add_i32 m0, s37, 0xc000
	s_nop 0
	global_load_lds_dwordx4 v[208:209], off
	v_lshl_add_u64 v[208:209], s[22:23], 0, v[144:145]
	s_add_i32 m0, s37, 0xe000
	s_nop 0
	global_load_lds_dwordx4 v[208:209], off
	s_waitcnt vmcnt(8)
	s_waitcnt lgkmcnt(0)
	s_barrier
	s_setprio 1
	s_waitcnt lgkmcnt(0)
	v_mfma_f32_16x16x32_f16 v[126:129], v[130:133], v[180:183], 0
	v_mfma_f32_16x16x32_f16 v[118:121], v[150:153], v[180:183], 0
	v_mfma_f32_16x16x32_f16 v[110:113], v[130:133], v[188:191], 0
	v_mfma_f32_16x16x32_f16 v[102:105], v[150:153], v[188:191], 0
	v_mfma_f32_16x16x32_f16 v[92:95], v[130:133], v[196:199], 0
	v_mfma_f32_16x16x32_f16 v[84:87], v[150:153], v[196:199], 0
	v_mfma_f32_16x16x32_f16 v[76:79], v[130:133], v[204:207], 0
	v_mfma_f32_16x16x32_f16 v[68:71], v[150:153], v[204:207], 0
	v_mfma_f32_16x16x32_f16 v[126:129], v[146:149], v[184:187], v[126:129]
	v_mfma_f32_16x16x32_f16 v[118:121], v[154:157], v[184:187], v[118:121]
	v_mfma_f32_16x16x32_f16 v[110:113], v[146:149], v[192:195], v[110:113]
	v_mfma_f32_16x16x32_f16 v[102:105], v[154:157], v[192:195], v[102:105]
	v_mfma_f32_16x16x32_f16 v[92:95], v[146:149], v[200:203], v[92:95]
	v_mfma_f32_16x16x32_f16 v[84:87], v[154:157], v[200:203], v[84:87]
	v_mfma_f32_16x16x32_f16 v[76:79], v[146:149], v[216:219], v[76:79]
	v_mfma_f32_16x16x32_f16 v[68:71], v[154:157], v[216:219], v[68:71]
	v_mfma_f32_16x16x32_f16 v[122:125], v[158:161], v[180:183], 0
	v_mfma_f32_16x16x32_f16 v[114:117], v[168:171], v[180:183], 0
	v_mfma_f32_16x16x32_f16 v[106:109], v[158:161], v[188:191], 0
	v_mfma_f32_16x16x32_f16 v[98:101], v[168:171], v[188:191], 0
	v_mfma_f32_16x16x32_f16 v[88:91], v[158:161], v[196:199], 0
	v_mfma_f32_16x16x32_f16 v[80:83], v[168:171], v[196:199], 0
	v_mfma_f32_16x16x32_f16 v[72:75], v[158:161], v[204:207], 0
	v_mfma_f32_16x16x32_f16 v[64:67], v[168:171], v[204:207], 0
	v_mfma_f32_16x16x32_f16 v[122:125], v[162:165], v[184:187], v[122:125]
	v_mfma_f32_16x16x32_f16 v[114:117], v[176:179], v[184:187], v[114:117]
	v_mfma_f32_16x16x32_f16 v[106:109], v[162:165], v[192:195], v[106:109]
	v_mfma_f32_16x16x32_f16 v[98:101], v[176:179], v[192:195], v[98:101]
	v_mfma_f32_16x16x32_f16 v[88:91], v[162:165], v[200:203], v[88:91]
	v_mfma_f32_16x16x32_f16 v[80:83], v[176:179], v[200:203], v[80:83]
	v_mfma_f32_16x16x32_f16 v[72:75], v[162:165], v[216:219], v[72:75]
	v_mfma_f32_16x16x32_f16 v[64:67], v[176:179], v[216:219], v[64:67]
	s_setprio 0
	s_barrier
	s_add_i32 s60, s60, s29
	v_lshl_add_u64 v[208:209], s[24:25], 0, v[96:97]
	s_mov_b32 m0, s60
	ds_read_b128 v[180:183], v175 offset:16384
	ds_read_b128 v[184:187], v175 offset:17408
	ds_read_b128 v[188:191], v175 offset:18432
	ds_read_b128 v[192:195], v175 offset:19456
	ds_read_b128 v[196:199], v175 offset:20480
	ds_read_b128 v[200:203], v175 offset:21504
	ds_read_b128 v[204:207], v175 offset:22528
	ds_read_b128 v[216:219], v175 offset:23552
	global_load_lds_dwordx4 v[208:209], off
	s_add_i32 m0, s60, 0x2000
	s_add_u32 s60, s24, 0x40000
	v_lshl_add_u64 v[210:211], s[24:25], 0, v[134:135]
	s_addc_u32 s61, s25, 0
	s_add_i32 s63, s63, s29
	global_load_lds_dwordx4 v[210:211], off
	v_lshl_add_u64 v[212:213], s[60:61], 0, v[96:97]
	s_mov_b32 m0, s63
	v_lshl_add_u64 v[220:221], s[26:27], 0, v[136:137]
	global_load_lds_dwordx4 v[212:213], off
	v_lshl_add_u64 v[212:213], s[60:61], 0, v[134:135]
	s_add_i32 m0, s63, 0x2000
	s_nop 0
	global_load_lds_dwordx4 v[212:213], off
	v_lshl_add_u64 v[212:213], s[26:27], 0, v[138:139]
	s_mov_b32 m0, s37
	s_nop 0
	global_load_lds_dwordx4 v[212:213], off
	s_mov_b32 m0, s45
	s_nop 0
	global_load_lds_dwordx4 v[220:221], off
	s_waitcnt vmcnt(8)
	s_waitcnt lgkmcnt(0)
	s_barrier
	s_setprio 1
	s_waitcnt lgkmcnt(0)
	v_mfma_f32_16x16x32_f16 v[60:63], v[130:133], v[180:183], 0
	v_mfma_f32_16x16x32_f16 v[52:55], v[150:153], v[180:183], 0
	v_mfma_f32_16x16x32_f16 v[44:47], v[130:133], v[188:191], 0
	v_mfma_f32_16x16x32_f16 v[36:39], v[150:153], v[188:191], 0
	v_mfma_f32_16x16x32_f16 v[28:31], v[130:133], v[196:199], 0
	v_mfma_f32_16x16x32_f16 v[20:23], v[150:153], v[196:199], 0
	v_mfma_f32_16x16x32_f16 v[12:15], v[130:133], v[204:207], 0
	v_mfma_f32_16x16x32_f16 v[4:7], v[150:153], v[204:207], 0
	v_mfma_f32_16x16x32_f16 v[60:63], v[146:149], v[184:187], v[60:63]
	v_mfma_f32_16x16x32_f16 v[52:55], v[154:157], v[184:187], v[52:55]
	v_mfma_f32_16x16x32_f16 v[44:47], v[146:149], v[192:195], v[44:47]
	v_mfma_f32_16x16x32_f16 v[36:39], v[154:157], v[192:195], v[36:39]
	v_mfma_f32_16x16x32_f16 v[28:31], v[146:149], v[200:203], v[28:31]
	v_mfma_f32_16x16x32_f16 v[20:23], v[154:157], v[200:203], v[20:23]
	v_mfma_f32_16x16x32_f16 v[12:15], v[146:149], v[216:219], v[12:15]
	v_mfma_f32_16x16x32_f16 v[4:7], v[154:157], v[216:219], v[4:7]
	v_mfma_f32_16x16x32_f16 v[56:59], v[158:161], v[180:183], 0
	v_mfma_f32_16x16x32_f16 v[48:51], v[168:171], v[180:183], 0
	v_mfma_f32_16x16x32_f16 v[40:43], v[158:161], v[188:191], 0
	v_mfma_f32_16x16x32_f16 v[32:35], v[168:171], v[188:191], 0
	v_mfma_f32_16x16x32_f16 v[24:27], v[158:161], v[196:199], 0
	v_mfma_f32_16x16x32_f16 v[16:19], v[168:171], v[196:199], 0
	v_mfma_f32_16x16x32_f16 v[8:11], v[158:161], v[204:207], 0
	v_mfma_f32_16x16x32_f16 v[0:3], v[168:171], v[204:207], 0
	v_mfma_f32_16x16x32_f16 v[56:59], v[162:165], v[184:187], v[56:59]
	v_mfma_f32_16x16x32_f16 v[48:51], v[176:179], v[184:187], v[48:51]
	v_mfma_f32_16x16x32_f16 v[40:43], v[162:165], v[192:195], v[40:43]
	v_mfma_f32_16x16x32_f16 v[32:35], v[176:179], v[192:195], v[32:35]
	v_mfma_f32_16x16x32_f16 v[24:27], v[162:165], v[200:203], v[24:27]
	v_mfma_f32_16x16x32_f16 v[16:19], v[176:179], v[200:203], v[16:19]
	v_mfma_f32_16x16x32_f16 v[8:11], v[162:165], v[216:219], v[8:11]
	v_mfma_f32_16x16x32_f16 v[0:3], v[176:179], v[216:219], v[0:3]
	s_setprio 0
	s_barrier
	s_add_i32 s60, 0, 0x18000
	s_add_i32 s61, 0, 0x1c000
	v_add_u32_e32 v154, s60, v172
	v_add_u32_e32 v176, s61, v172
	ds_read_b128 v[130:133], v154
	ds_read_b128 v[146:149], v154 offset:1024
	ds_read_b128 v[150:153], v154 offset:2048
	ds_read_b128 v[154:157], v154 offset:3072
	ds_read_b128 v[158:161], v176
	ds_read_b128 v[162:165], v176 offset:1024
	ds_read_b128 v[168:171], v176 offset:2048
	ds_read_b128 v[176:179], v176 offset:3072
	s_add_u32 s26, s26, 0x40000
	s_addc_u32 s27, s27, 0
	s_mov_b32 m0, s46
	v_lshl_add_u64 v[222:223], s[26:27], 0, v[138:139]
	ds_read_b128 v[180:183], v175 offset:32768
	ds_read_b128 v[184:187], v175 offset:33792
	ds_read_b128 v[188:191], v175 offset:34816
	ds_read_b128 v[192:195], v175 offset:35840
	ds_read_b128 v[196:199], v175 offset:36864
	ds_read_b128 v[200:203], v175 offset:37888
	ds_read_b128 v[204:207], v175 offset:38912
	ds_read_b128 v[216:219], v175 offset:39936
	global_load_lds_dwordx4 v[222:223], off
	v_lshl_add_u64 v[222:223], s[26:27], 0, v[136:137]
	s_mov_b32 m0, s47
	s_nop 0
	global_load_lds_dwordx4 v[222:223], off
	s_waitcnt vmcnt(8)
	s_waitcnt lgkmcnt(0)
	s_barrier
	s_setprio 1
	s_waitcnt lgkmcnt(0)
	v_mfma_f32_16x16x32_f16 v[126:129], v[130:133], v[180:183], v[126:129]
	v_mfma_f32_16x16x32_f16 v[118:121], v[150:153], v[180:183], v[118:121]
	v_mfma_f32_16x16x32_f16 v[110:113], v[130:133], v[188:191], v[110:113]
	v_mfma_f32_16x16x32_f16 v[102:105], v[150:153], v[188:191], v[102:105]
	v_mfma_f32_16x16x32_f16 v[92:95], v[130:133], v[196:199], v[92:95]
	v_mfma_f32_16x16x32_f16 v[84:87], v[150:153], v[196:199], v[84:87]
	v_mfma_f32_16x16x32_f16 v[76:79], v[130:133], v[204:207], v[76:79]
	v_mfma_f32_16x16x32_f16 v[68:71], v[150:153], v[204:207], v[68:71]
	v_mfma_f32_16x16x32_f16 v[126:129], v[146:149], v[184:187], v[126:129]
	v_mfma_f32_16x16x32_f16 v[118:121], v[154:157], v[184:187], v[118:121]
	v_mfma_f32_16x16x32_f16 v[110:113], v[146:149], v[192:195], v[110:113]
	v_mfma_f32_16x16x32_f16 v[102:105], v[154:157], v[192:195], v[102:105]
	v_mfma_f32_16x16x32_f16 v[92:95], v[146:149], v[200:203], v[92:95]
	v_mfma_f32_16x16x32_f16 v[84:87], v[154:157], v[200:203], v[84:87]
	v_mfma_f32_16x16x32_f16 v[76:79], v[146:149], v[216:219], v[76:79]
	v_mfma_f32_16x16x32_f16 v[68:71], v[154:157], v[216:219], v[68:71]
	v_mfma_f32_16x16x32_f16 v[122:125], v[158:161], v[180:183], v[122:125]
	v_mfma_f32_16x16x32_f16 v[114:117], v[168:171], v[180:183], v[114:117]
	v_mfma_f32_16x16x32_f16 v[106:109], v[158:161], v[188:191], v[106:109]
	v_mfma_f32_16x16x32_f16 v[98:101], v[168:171], v[188:191], v[98:101]
	v_mfma_f32_16x16x32_f16 v[88:91], v[158:161], v[196:199], v[88:91]
	v_mfma_f32_16x16x32_f16 v[80:83], v[168:171], v[196:199], v[80:83]
	v_mfma_f32_16x16x32_f16 v[72:75], v[158:161], v[204:207], v[72:75]
	v_mfma_f32_16x16x32_f16 v[64:67], v[168:171], v[204:207], v[64:67]
	v_mfma_f32_16x16x32_f16 v[122:125], v[162:165], v[184:187], v[122:125]
	v_mfma_f32_16x16x32_f16 v[114:117], v[176:179], v[184:187], v[114:117]
	v_mfma_f32_16x16x32_f16 v[106:109], v[162:165], v[192:195], v[106:109]
	v_mfma_f32_16x16x32_f16 v[98:101], v[176:179], v[192:195], v[98:101]
	v_mfma_f32_16x16x32_f16 v[88:91], v[162:165], v[200:203], v[88:91]
	v_mfma_f32_16x16x32_f16 v[80:83], v[176:179], v[200:203], v[80:83]
	v_mfma_f32_16x16x32_f16 v[72:75], v[162:165], v[216:219], v[72:75]
	v_mfma_f32_16x16x32_f16 v[64:67], v[176:179], v[216:219], v[64:67]
	s_setprio 0
	s_barrier
	s_add_i32 s26, s60, s29
	v_lshl_add_u64 v[208:209], v[208:209], 0, s[94:95]
	s_mov_b32 m0, s26
	ds_read_b128 v[180:183], v175 offset:49152
	ds_read_b128 v[184:187], v175 offset:50176
	ds_read_b128 v[188:191], v175 offset:51200
	ds_read_b128 v[192:195], v175 offset:52224
	ds_read_b128 v[196:199], v175 offset:53248
	ds_read_b128 v[200:203], v175 offset:54272
	ds_read_b128 v[204:207], v175 offset:55296
	ds_read_b128 v[216:219], v175 offset:56320
	global_load_lds_dwordx4 v[208:209], off
	s_add_i32 m0, s26, 0x2000
	s_add_u32 s24, s24, 0x40080
	v_lshl_add_u64 v[208:209], v[210:211], 0, s[94:95]
	s_addc_u32 s25, s25, 0
	s_add_i32 s26, s61, s29
	global_load_lds_dwordx4 v[208:209], off
	v_lshl_add_u64 v[208:209], s[24:25], 0, v[96:97]
	s_mov_b32 m0, s26
	s_nop 0
	global_load_lds_dwordx4 v[208:209], off
	v_lshl_add_u64 v[208:209], s[24:25], 0, v[134:135]
	s_add_i32 m0, s26, 0x2000
	s_nop 0
	global_load_lds_dwordx4 v[208:209], off
	v_lshl_add_u64 v[208:209], v[212:213], 0, s[94:95]
	s_mov_b32 m0, s48
	s_nop 0
	global_load_lds_dwordx4 v[208:209], off
	v_lshl_add_u64 v[208:209], v[220:221], 0, s[94:95]
	s_mov_b32 m0, s49
	s_nop 0
	global_load_lds_dwordx4 v[208:209], off
	s_waitcnt vmcnt(8)
	s_waitcnt lgkmcnt(0)
	s_barrier
	s_setprio 1
	s_waitcnt lgkmcnt(0)
	v_mfma_f32_16x16x32_f16 v[60:63], v[130:133], v[180:183], v[60:63]
	v_mfma_f32_16x16x32_f16 v[52:55], v[150:153], v[180:183], v[52:55]
	v_mfma_f32_16x16x32_f16 v[44:47], v[130:133], v[188:191], v[44:47]
	v_mfma_f32_16x16x32_f16 v[36:39], v[150:153], v[188:191], v[36:39]
	v_mfma_f32_16x16x32_f16 v[28:31], v[130:133], v[196:199], v[28:31]
	v_mfma_f32_16x16x32_f16 v[20:23], v[150:153], v[196:199], v[20:23]
	v_mfma_f32_16x16x32_f16 v[12:15], v[130:133], v[204:207], v[12:15]
	v_mfma_f32_16x16x32_f16 v[4:7], v[150:153], v[204:207], v[4:7]
	v_mfma_f32_16x16x32_f16 v[60:63], v[146:149], v[184:187], v[60:63]
	v_mfma_f32_16x16x32_f16 v[52:55], v[154:157], v[184:187], v[52:55]
	v_mfma_f32_16x16x32_f16 v[44:47], v[146:149], v[192:195], v[44:47]
	v_mfma_f32_16x16x32_f16 v[36:39], v[154:157], v[192:195], v[36:39]
	v_mfma_f32_16x16x32_f16 v[28:31], v[146:149], v[200:203], v[28:31]
	v_mfma_f32_16x16x32_f16 v[20:23], v[154:157], v[200:203], v[20:23]
	v_mfma_f32_16x16x32_f16 v[12:15], v[146:149], v[216:219], v[12:15]
	v_mfma_f32_16x16x32_f16 v[4:7], v[154:157], v[216:219], v[4:7]
	v_mfma_f32_16x16x32_f16 v[56:59], v[158:161], v[180:183], v[56:59]
	v_mfma_f32_16x16x32_f16 v[48:51], v[168:171], v[180:183], v[48:51]
	v_mfma_f32_16x16x32_f16 v[40:43], v[158:161], v[188:191], v[40:43]
	v_mfma_f32_16x16x32_f16 v[32:35], v[168:171], v[188:191], v[32:35]
	v_mfma_f32_16x16x32_f16 v[24:27], v[158:161], v[196:199], v[24:27]
	v_mfma_f32_16x16x32_f16 v[16:19], v[168:171], v[196:199], v[16:19]
	v_mfma_f32_16x16x32_f16 v[8:11], v[158:161], v[204:207], v[8:11]
	v_mfma_f32_16x16x32_f16 v[0:3], v[168:171], v[204:207], v[0:3]
	v_mfma_f32_16x16x32_f16 v[56:59], v[162:165], v[184:187], v[56:59]
	v_mfma_f32_16x16x32_f16 v[48:51], v[176:179], v[184:187], v[48:51]
	v_mfma_f32_16x16x32_f16 v[40:43], v[162:165], v[192:195], v[40:43]
	v_mfma_f32_16x16x32_f16 v[32:35], v[176:179], v[192:195], v[32:35]
	v_mfma_f32_16x16x32_f16 v[24:27], v[162:165], v[200:203], v[24:27]
	v_mfma_f32_16x16x32_f16 v[16:19], v[176:179], v[200:203], v[16:19]
	v_mfma_f32_16x16x32_f16 v[8:11], v[162:165], v[216:219], v[8:11]
	v_mfma_f32_16x16x32_f16 v[0:3], v[176:179], v[216:219], v[0:3]
	s_setprio 0
	s_barrier
	s_add_i32 s57, s57, 2
	s_add_u32 s22, s22, 0x100
	s_addc_u32 s23, s23, 0
	s_add_u32 s55, s55, 0x100
	s_addc_u32 s56, s56, 0
	s_cmp_gt_u32 s57, 13
	s_cbranch_scc0 .LBB0_68
	s_branch .Lz68_exit
